# v16 + LayerNorm loops: the lane-index computations of the former ds_bpermute butterflies deleted (about 30 VALU per row)
# baseline (speedup 1.0000x reference)
; DI void wave_sum2(float& a, float& b) {
; #pragma unroll
;     for (int o = 1; o < 64; o <<= 1) { const float ta = __shfl_xor(a, o), tb = __shfl_xor(b, o); a += ta; b += tb; }
; }
; DI void lnmod_phase(const Args& A, LAS unsigned char* lds, int tid, int bid, int G, bool init, int l_norm, int i_norm, int l_mod, int i_mod, bool want_dt, int nrows, bool ctx_partial, const float* gprev, const float* bprev) {
;     ...
;             float s = 0.f, s2 = 0.f;
; #pragma unroll
;             for (int j = 0; j < 4; ++j) { s += (v[j].x + v[j].y) + (v[j].z + v[j].w); s2 += (v[j].x * v[j].x + v[j].y * v[j].y) + (v[j].z * v[j].z + v[j].w * v[j].w); }
;             wave_sum2(s, s2);
;             const float mean = s * (1.f / DM);
;             const float rstd = 1.0f / sqrtf(fmaxf(s2 * (1.f / DM) - mean * mean, 0.f) + 1e-5f);
; #pragma unroll
;             for (int j = 0; j < 4; ++j) v[j] = v[j] - mean;
;             if (l_mod >= 0 && lane == 0) STAT[row] = (f32x2){mean, rstd};
.LBB0_209:
	s_or_b64 exec, exec, s[6:7]
	s_andn2_b64 vcc, exec, s[8:9]
	s_cbranch_vccnz .Llnl1_bypass
	v_pk_add_f32 v[110:111], v[106:107], v[90:91]
	v_mul_f32_e32 v99, v91, v91
	v_add_f32_e32 v87, v110, v111
	v_add_f32_e32 v109, 0, v87
	v_mul_f32_e32 v87, v106, v106
	v_fmac_f32_e32 v87, v90, v90
	v_fmac_f32_e32 v99, v107, v107
	v_add_f32_e32 v87, v87, v99
	v_mul_f32_e32 v99, v102, v102
	v_mul_f32_e32 v101, v93, v93
	v_pk_add_f32 v[110:111], v[102:103], v[92:93]
	v_fmac_f32_e32 v99, v92, v92
	v_fmac_f32_e32 v101, v103, v103
	v_pk_add_f32 v[110:111], v[110:111], v[110:111] op_sel_hi:[0,1]
	v_add_f32_e32 v99, v99, v101
	v_add_f32_e32 v87, v87, v99
	v_mul_f32_e32 v99, v97, v97
	v_mul_f32_e32 v110, v95, v95
	v_add_f32_e32 v101, v96, v97
	v_add_f32_e32 v105, v94, v95
	v_fmac_f32_e32 v99, v96, v96
	v_fmac_f32_e32 v110, v94, v94
	v_add_f32_e32 v99, v99, v110
	v_pk_add_f32 v[112:113], v[100:101], v[104:105]
	v_mul_f32_e32 v101, v104, v104
	v_mul_f32_e32 v105, v108, v108
	v_add_f32_e32 v87, v99, v87
	v_mov_b32_e32 v99, v111
	v_fmac_f32_e32 v101, v100, v100
	v_fmac_f32_e32 v105, v98, v98
	v_pk_add_f32 v[110:111], v[98:99], v[108:109]
	v_add_f32_e32 v101, v101, v105
	v_pk_add_f32 v[110:111], v[112:113], v[110:111]
	v_add_f32_e32 v87, v101, v87
	v_add_f32_e32 v99, v110, v111
	v_add_u32_e32 v110, 64, v101
	s_mov_b32 s6, 0x3a800000
	s_nop 0
	s_nop 1
	v_mov_b32_dpp v101, v99 quad_perm:[1,0,3,2] row_mask:0xf bank_mask:0xf
	v_mov_b32_dpp v105, v87 quad_perm:[1,0,3,2] row_mask:0xf bank_mask:0xf
	s_waitcnt lgkmcnt(1)
	v_add_f32_e32 v99, v99, v101
	s_waitcnt lgkmcnt(0)
	v_add_f32_e32 v87, v87, v105
	s_nop 1
	v_mov_b32_dpp v101, v99 quad_perm:[2,3,0,1] row_mask:0xf bank_mask:0xf
	v_mov_b32_dpp v105, v87 quad_perm:[2,3,0,1] row_mask:0xf bank_mask:0xf
	s_waitcnt lgkmcnt(1)
	v_add_f32_e32 v99, v99, v101
	s_waitcnt lgkmcnt(0)
	v_add_f32_e32 v87, v87, v105
	s_nop 1
	v_mov_b32_dpp v101, v99 row_half_mirror row_mask:0xf bank_mask:0xf
	v_mov_b32_dpp v105, v87 row_half_mirror row_mask:0xf bank_mask:0xf
	s_waitcnt lgkmcnt(1)
	v_add_f32_e32 v99, v99, v101
	s_waitcnt lgkmcnt(0)
	v_add_f32_e32 v87, v87, v105
	s_nop 1
	v_mov_b32_dpp v101, v99 row_mirror row_mask:0xf bank_mask:0xf
	v_mov_b32_dpp v112, v87 row_mirror row_mask:0xf bank_mask:0xf
	s_waitcnt lgkmcnt(1)
	v_add_f32_e32 v99, v99, v101
	s_waitcnt lgkmcnt(0)
	v_add_f32_e32 v87, v87, v112
	v_mov_b32_e32 v112, v99
	v_mov_b32_e32 v113, v87
	s_nop 1
	v_permlane16_swap_b32_e32 v99, v112
	v_permlane16_swap_b32_e32 v87, v113
	s_waitcnt lgkmcnt(1)
	v_add_f32_e32 v112, v99, v112
	s_waitcnt lgkmcnt(0)
	v_add_f32_e32 v87, v87, v113
	v_mov_b32_e32 v110, v112
	v_mov_b32_e32 v113, v87
	s_nop 1
	v_permlane32_swap_b32_e32 v112, v110
	v_permlane32_swap_b32_e32 v87, v113
	s_waitcnt lgkmcnt(1)
	v_add_f32_e32 v110, v112, v110
	v_mul_f32_e32 v112, 0x3a800000, v110
	s_waitcnt lgkmcnt(0)
	v_add_f32_e32 v87, v87, v113
	v_mul_f32_e32 v110, v112, v112
	v_fma_f32 v87, v87, s6, -v110
	v_max_f32_e32 v87, 0, v87
	v_add_f32_e32 v87, 0x3727c5ac, v87
	v_mul_f32_e32 v110, 0x4f800000, v87
	v_cmp_gt_f32_e32 vcc, s65, v87
	s_nop 1
	v_cndmask_b32_e32 v87, v87, v110, vcc
	v_sqrt_f32_e32 v110, v87
	s_nop 0
	v_add_u32_e32 v113, -1, v110
	v_fma_f32 v115, -v113, v110, v87
	v_cmp_ge_f32_e64 s[6:7], 0, v115
	v_add_u32_e32 v115, 1, v110
	s_nop 0
	v_cndmask_b32_e64 v113, v110, v113, s[6:7]
	v_fma_f32 v110, -v115, v110, v87
	v_cmp_lt_f32_e64 s[6:7], 0, v110
	s_nop 1
	v_cndmask_b32_e64 v110, v113, v115, s[6:7]
	v_mul_f32_e32 v113, 0x37800000, v110
	v_cndmask_b32_e32 v110, v110, v113, vcc
	v_cmp_class_f32_e32 vcc, v87, v208
	s_nop 1
	v_cndmask_b32_e32 v87, v110, v87, vcc
	v_div_scale_f32 v110, s[6:7], v87, v87, 1.0
	v_rcp_f32_e32 v113, v110
	s_nop 0
	v_fma_f32 v115, -v110, v113, 1.0
	v_fmac_f32_e32 v113, v115, v113
	v_div_scale_f32 v115, vcc, 1.0, v87, 1.0
	v_mul_f32_e32 v118, v115, v113
	v_fma_f32 v119, -v110, v118, v115
	v_fmac_f32_e32 v118, v119, v113
	v_fma_f32 v110, -v110, v118, v115
	v_div_fmas_f32 v110, v110, v113, v118
	v_div_fixup_f32 v110, v110, v87, 1.0
	s_and_saveexec_b64 s[6:7], s[20:21]
	s_cbranch_execz .LBB0_212
	v_readlane_b32 s36, v253, 23
	v_readlane_b32 s38, v253, 25
	v_readlane_b32 s39, v253, 26
	v_mov_b32_e32 v113, v110
	v_readlane_b32 s37, v253, 24
	v_lshl_add_u64 v[118:119], s[38:39], 0, v[74:75]
	global_store_dwordx2 v[118:119], v[112:113], off

; DI void wave_sum2(float& a, float& b) {
; #pragma unroll
;     for (int o = 1; o < 64; o <<= 1) { const float ta = __shfl_xor(a, o), tb = __shfl_xor(b, o); a += ta; b += tb; }
; }
; DI void lnmod_phase(const Args& A, LAS unsigned char* lds, int tid, int bid, int G, bool init, int l_norm, int i_norm, int l_mod, int i_mod, bool want_dt, int nrows, bool ctx_partial, const float* gprev, const float* bprev) {
;     ...
;         if (l_norm >= 0) {
;             float s = 0.f, s2 = 0.f;
; #pragma unroll
;             for (int j = 0; j < 4; ++j) { s += (v[j].x + v[j].y) + (v[j].z + v[j].w); s2 += (v[j].x * v[j].x + v[j].y * v[j].y) + (v[j].z * v[j].z + v[j].w * v[j].w); }
;             wave_sum2(s, s2);
;             const float mean = s * (1.f / DM);
;             const float rstd = 1.0f / sqrtf(fmaxf(s2 * (1.f / DM) - mean * mean, 0.f) + 1e-5f);
; #pragma unroll
;             for (int j = 0; j < 4; ++j) v[j] = v[j] - mean;
;             if (l_mod >= 0 && lane == 0) STAT[row] = (f32x2){mean, rstd};
.LBB0_233:
	s_or_b64 exec, exec, s[4:5]
	s_andn2_b64 vcc, exec, s[2:3]
	s_cbranch_vccnz .LBB0_237
	v_pk_add_f32 v[110:111], v[108:109], v[64:65]
	v_mul_f32_e32 v77, v65, v65
	v_add_f32_e32 v71, v110, v111
	v_add_f32_e32 v107, 0, v71
	v_mul_f32_e32 v71, v108, v108
	v_fmac_f32_e32 v71, v64, v64
	v_fmac_f32_e32 v77, v109, v109
	v_pk_add_f32 v[110:111], v[66:67], v[68:69]
	v_add_f32_e32 v71, v71, v77
	v_pk_add_f32 v[110:111], v[110:111], v[110:111] op_sel_hi:[0,1]
	v_mul_f32_e32 v77, v66, v66
	v_mul_f32_e32 v79, v69, v69
	v_fmac_f32_e32 v77, v68, v68
	v_fmac_f32_e32 v79, v67, v67
	v_mul_f32_e32 v110, v73, v73
	v_mul_f32_e32 v112, v75, v75
	v_add_f32_e32 v77, v77, v79
	v_fmac_f32_e32 v110, v72, v72
	v_fmac_f32_e32 v112, v74, v74
	v_add_f32_e32 v79, v71, v77
	v_add_f32_e32 v110, v110, v112
	v_add_f32_e32 v77, v72, v73
	v_add_f32_e32 v71, v74, v75
	v_add_f32_e32 v114, v110, v79
	v_mov_b32_e32 v79, v111
	v_pk_add_f32 v[112:113], v[76:77], v[70:71]
	v_pk_add_f32 v[110:111], v[78:79], v[106:107]
	v_mul_f32_e32 v77, v70, v70
	v_mul_f32_e32 v79, v106, v106
	v_fmac_f32_e32 v77, v76, v76
	v_fmac_f32_e32 v79, v78, v78
	v_add_f32_e32 v77, v77, v79
	v_pk_add_f32 v[110:111], v[112:113], v[110:111]
	v_add_f32_e32 v77, v77, v114
	v_add_f32_e32 v71, v110, v111
	s_nop 1
	v_mov_b32_dpp v110, v71 quad_perm:[1,0,3,2] row_mask:0xf bank_mask:0xf
	v_mov_b32_dpp v107, v77 quad_perm:[1,0,3,2] row_mask:0xf bank_mask:0xf
	s_mov_b32 s4, 0x3a800000
	s_waitcnt lgkmcnt(1)
	v_add_f32_e32 v71, v71, v110
	s_waitcnt lgkmcnt(0)
	v_add_f32_e32 v77, v77, v107
	s_nop 1
	v_mov_b32_dpp v110, v71 quad_perm:[2,3,0,1] row_mask:0xf bank_mask:0xf
	v_mov_b32_dpp v107, v77 quad_perm:[2,3,0,1] row_mask:0xf bank_mask:0xf
	s_waitcnt lgkmcnt(1)
	v_add_f32_e32 v71, v71, v110
	s_waitcnt lgkmcnt(0)
	v_add_f32_e32 v77, v77, v107
	s_nop 1
	v_mov_b32_dpp v110, v71 row_half_mirror row_mask:0xf bank_mask:0xf
	v_mov_b32_dpp v107, v77 row_half_mirror row_mask:0xf bank_mask:0xf
	s_waitcnt lgkmcnt(1)
	v_add_f32_e32 v71, v71, v110
	s_waitcnt lgkmcnt(0)
	v_add_f32_e32 v77, v77, v107
	s_nop 1
	v_mov_b32_dpp v110, v71 row_mirror row_mask:0xf bank_mask:0xf
	v_mov_b32_dpp v107, v77 row_mirror row_mask:0xf bank_mask:0xf
	s_waitcnt lgkmcnt(1)
	v_add_f32_e32 v71, v71, v110
	s_waitcnt lgkmcnt(0)
	v_add_f32_e32 v77, v77, v107
	v_mov_b32_e32 v110, v71
	v_mov_b32_e32 v107, v77
	s_nop 1
	v_permlane16_swap_b32_e32 v71, v110
	v_permlane16_swap_b32_e32 v77, v107
	s_waitcnt lgkmcnt(1)
	v_add_f32_e32 v71, v71, v110
	s_waitcnt lgkmcnt(0)
	v_add_f32_e32 v77, v77, v107
	v_mov_b32_e32 v107, v71
	v_mov_b32_e32 v79, v77
	s_nop 1
	v_permlane32_swap_b32_e32 v71, v107
	v_permlane32_swap_b32_e32 v77, v79
	s_waitcnt lgkmcnt(1)
	v_add_f32_e32 v71, v71, v107
	v_mul_f32_e32 v112, 0x3a800000, v71
	s_waitcnt lgkmcnt(0)
	v_add_f32_e32 v77, v77, v79
	v_mul_f32_e32 v71, v112, v112
	v_fma_f32 v71, v77, s4, -v71
	v_max_f32_e32 v71, 0, v71
	v_add_f32_e32 v71, 0x3727c5ac, v71
	v_mul_f32_e32 v77, 0x4f800000, v71
	v_cmp_gt_f32_e32 vcc, s65, v71
	s_nop 1
	v_cndmask_b32_e32 v71, v71, v77, vcc
	v_sqrt_f32_e32 v77, v71
	s_nop 0
	v_add_u32_e32 v79, -1, v77
	v_fma_f32 v107, -v79, v77, v71
	v_cmp_ge_f32_e64 s[4:5], 0, v107
	v_add_u32_e32 v107, 1, v77
	s_nop 0
	v_cndmask_b32_e64 v79, v77, v79, s[4:5]
	v_fma_f32 v77, -v107, v77, v71
	v_cmp_lt_f32_e64 s[4:5], 0, v77
	s_nop 1
	v_cndmask_b32_e64 v77, v79, v107, s[4:5]
	v_mul_f32_e32 v79, 0x37800000, v77
	v_cndmask_b32_e32 v77, v77, v79, vcc
	v_cmp_class_f32_e32 vcc, v71, v208
	s_nop 1
	v_cndmask_b32_e32 v71, v77, v71, vcc
	v_div_scale_f32 v77, s[4:5], v71, v71, 1.0
	v_rcp_f32_e32 v79, v77
	s_nop 0
	v_fma_f32 v107, -v77, v79, 1.0
	v_fmac_f32_e32 v79, v107, v79
	v_div_scale_f32 v107, vcc, 1.0, v71, 1.0
	v_mul_f32_e32 v110, v107, v79
	v_fma_f32 v111, -v77, v110, v107
	v_fmac_f32_e32 v110, v111, v79
	v_fma_f32 v77, -v77, v110, v107
	v_div_fmas_f32 v77, v77, v79, v110
	v_div_fixup_f32 v110, v77, v71, 1.0
	s_and_saveexec_b64 s[4:5], s[18:19]
	s_cbranch_execz .LBB0_236
	v_readlane_b32 s36, v253, 23
	v_readlane_b32 s38, v253, 25
	v_readlane_b32 s39, v253, 26
	v_mov_b32_e32 v113, v110
	v_readlane_b32 s37, v253, 24
	v_lshl_add_u64 v[114:115], s[38:39], 0, v[92:93]
	global_store_dwordx2 v[114:115], v[112:113], off

; DI void wave_sum2(float& a, float& b) {
; #pragma unroll
;     for (int o = 1; o < 64; o <<= 1) { const float ta = __shfl_xor(a, o), tb = __shfl_xor(b, o); a += ta; b += tb; }
; }
; DI void lnmod_phase(const Args& A, LAS unsigned char* lds, int tid, int bid, int G, bool init, int l_norm, int i_norm, int l_mod, int i_mod, bool want_dt, int nrows, bool ctx_partial, const float* gprev, const float* bprev) {
;     ...
;         if (l_norm >= 0) {
;             float s = 0.f, s2 = 0.f;
; #pragma unroll
;             for (int j = 0; j < 4; ++j) { s += (v[j].x + v[j].y) + (v[j].z + v[j].w); s2 += (v[j].x * v[j].x + v[j].y * v[j].y) + (v[j].z * v[j].z + v[j].w * v[j].w); }
;             wave_sum2(s, s2);
;             const float mean = s * (1.f / DM);
;             const float rstd = 1.0f / sqrtf(fmaxf(s2 * (1.f / DM) - mean * mean, 0.f) + 1e-5f);
; #pragma unroll
;             for (int j = 0; j < 4; ++j) v[j] = v[j] - mean;
;             if (l_mod >= 0 && lane == 0) STAT[row] = (f32x2){mean, rstd};
.LBB0_284:
	s_or_b64 exec, exec, s[4:5]
	s_andn2_b64 vcc, exec, s[2:3]
	s_cbranch_vccnz .Llnl3_bypass
	v_pk_add_f32 v[108:109], v[104:105], v[88:89]
	v_mul_f32_e32 v99, v89, v89
	v_add_f32_e32 v97, v108, v109
	v_add_f32_e32 v107, 0, v97
	v_mul_f32_e32 v97, v104, v104
	v_fmac_f32_e32 v97, v88, v88
	v_fmac_f32_e32 v99, v105, v105
	v_add_f32_e32 v97, v97, v99
	v_pk_add_f32 v[108:109], v[100:101], v[90:91]
	v_mul_f32_e32 v99, v100, v100
	v_mul_f32_e32 v103, v91, v91
	v_pk_add_f32 v[108:109], v[108:109], v[108:109] op_sel_hi:[0,1]
	v_fmac_f32_e32 v99, v90, v90
	v_fmac_f32_e32 v103, v101, v101
	v_add_f32_e32 v99, v99, v103
	v_mul_f32_e32 v108, v95, v95
	v_mul_f32_e32 v110, v93, v93
	v_add_f32_e32 v97, v97, v99
	v_add_f32_e32 v99, v94, v95
	v_add_f32_e32 v103, v92, v93
	v_fmac_f32_e32 v108, v94, v94
	v_fmac_f32_e32 v110, v92, v92
	v_add_f32_e32 v108, v108, v110
	v_pk_add_f32 v[110:111], v[98:99], v[102:103]
	v_mul_f32_e32 v99, v102, v102
	v_mul_f32_e32 v103, v106, v106
	v_fmac_f32_e32 v99, v98, v98
	v_fmac_f32_e32 v103, v96, v96
	v_add_f32_e32 v112, v108, v97
	v_mov_b32_e32 v97, v109
	v_add_f32_e32 v99, v99, v103
	v_pk_add_f32 v[108:109], v[96:97], v[106:107]
	v_pk_add_f32 v[108:109], v[110:111], v[108:109]
	v_add_f32_e32 v99, v99, v112
	v_add_f32_e32 v97, v108, v109
	s_nop 1
	v_mov_b32_dpp v108, v97 quad_perm:[1,0,3,2] row_mask:0xf bank_mask:0xf
	v_mov_b32_dpp v107, v99 quad_perm:[1,0,3,2] row_mask:0xf bank_mask:0xf
	s_mov_b32 s4, 0x3a800000
	s_waitcnt lgkmcnt(1)
	v_add_f32_e32 v97, v97, v108
	s_waitcnt lgkmcnt(0)
	v_add_f32_e32 v99, v99, v107
	s_nop 1
	v_mov_b32_dpp v108, v97 quad_perm:[2,3,0,1] row_mask:0xf bank_mask:0xf
	v_mov_b32_dpp v107, v99 quad_perm:[2,3,0,1] row_mask:0xf bank_mask:0xf
	s_waitcnt lgkmcnt(1)
	v_add_f32_e32 v97, v97, v108
	s_waitcnt lgkmcnt(0)
	v_add_f32_e32 v99, v99, v107
	s_nop 1
	v_mov_b32_dpp v108, v97 row_half_mirror row_mask:0xf bank_mask:0xf
	v_mov_b32_dpp v107, v99 row_half_mirror row_mask:0xf bank_mask:0xf
	s_waitcnt lgkmcnt(1)
	v_add_f32_e32 v97, v97, v108
	s_waitcnt lgkmcnt(0)
	v_add_f32_e32 v99, v99, v107
	s_nop 1
	v_mov_b32_dpp v108, v97 row_mirror row_mask:0xf bank_mask:0xf
	v_mov_b32_dpp v107, v99 row_mirror row_mask:0xf bank_mask:0xf
	s_waitcnt lgkmcnt(1)
	v_add_f32_e32 v97, v97, v108
	s_waitcnt lgkmcnt(0)
	v_add_f32_e32 v99, v99, v107
	v_mov_b32_e32 v108, v97
	v_mov_b32_e32 v107, v99
	s_nop 1
	v_permlane16_swap_b32_e32 v97, v108
	v_permlane16_swap_b32_e32 v99, v107
	s_waitcnt lgkmcnt(1)
	v_add_f32_e32 v97, v97, v108
	s_waitcnt lgkmcnt(0)
	v_add_f32_e32 v99, v99, v107
	v_mov_b32_e32 v107, v97
	v_mov_b32_e32 v103, v99
	s_nop 1
	v_permlane32_swap_b32_e32 v97, v107
	v_permlane32_swap_b32_e32 v99, v103
	s_waitcnt lgkmcnt(1)
	v_add_f32_e32 v97, v97, v107
	v_mul_f32_e32 v110, 0x3a800000, v97
	s_waitcnt lgkmcnt(0)
	v_add_f32_e32 v99, v99, v103
	v_mul_f32_e32 v97, v110, v110
	v_fma_f32 v97, v99, s4, -v97
	v_max_f32_e32 v97, 0, v97
	v_add_f32_e32 v97, 0x3727c5ac, v97
	v_mul_f32_e32 v99, 0x4f800000, v97
	v_cmp_gt_f32_e32 vcc, s65, v97
	s_nop 1
	v_cndmask_b32_e32 v97, v97, v99, vcc
	v_sqrt_f32_e32 v99, v97
	s_nop 0
	v_add_u32_e32 v103, -1, v99
	v_fma_f32 v107, -v103, v99, v97
	v_cmp_ge_f32_e64 s[4:5], 0, v107
	v_add_u32_e32 v107, 1, v99
	s_nop 0
	v_cndmask_b32_e64 v103, v99, v103, s[4:5]
	v_fma_f32 v99, -v107, v99, v97
	v_cmp_lt_f32_e64 s[4:5], 0, v99
	s_nop 1
	v_cndmask_b32_e64 v99, v103, v107, s[4:5]
	v_mul_f32_e32 v103, 0x37800000, v99
	v_cndmask_b32_e32 v99, v99, v103, vcc
	v_cmp_class_f32_e32 vcc, v97, v208
	s_nop 1
	v_cndmask_b32_e32 v97, v99, v97, vcc
	v_div_scale_f32 v99, s[4:5], v97, v97, 1.0
	v_rcp_f32_e32 v103, v99
	s_nop 0
	v_fma_f32 v107, -v99, v103, 1.0
	v_fmac_f32_e32 v103, v107, v103
	v_div_scale_f32 v107, vcc, 1.0, v97, 1.0
	v_mul_f32_e32 v108, v107, v103
	v_fma_f32 v109, -v99, v108, v107
	v_fmac_f32_e32 v108, v109, v103
	v_fma_f32 v99, -v99, v108, v107
	v_div_fmas_f32 v99, v99, v103, v108
	v_div_fixup_f32 v108, v99, v97, 1.0
	s_and_saveexec_b64 s[4:5], s[14:15]
	s_cbranch_execz .LBB0_287
	v_readlane_b32 s24, v253, 23
	v_readlane_b32 s26, v253, 25
	v_readlane_b32 s27, v253, 26
	v_mov_b32_e32 v111, v108
	v_readlane_b32 s25, v253, 24
	v_lshl_add_u64 v[112:113], s[26:27], 0, v[74:75]
	global_store_dwordx2 v[112:113], v[110:111], off
